# diff attention: next-step K/V addresses and pointer advances computed in PV-gap MFMA shadow; step heads and step-B tail without 64-bit address arithmetic
# baseline (speedup 1.0000x reference)
; #define LAS __attribute__((address_space(3)))
; #define ATT_LOADK(t) do { \
;         int kr_ = kv_lo + (t) * 64 + lane; if constexpr (DIL) kr_ = kr_ < 0 ? 0 : (kr_ >= nseq ? nseq - 1 : kr_); \
;         sk0 = *(const u32x4*)(K0 + (size_t)kr_ * (size_t)(SK0 * dl) + wid * 8); \
;         if constexpr (DQK == 96) { if (wid < 4) sk1 = *(const u32x4*)(K1 + (size_t)kr_ * (size_t)(SK1 * dl) + wid * 8); } \
;     } while (0)
; #define ATT_STOREK(b) do { LAS unsigned char* kb_ = lds + KB0 + (b) * KBSZ; \
;         *(LAS u32x4*)(kb_ + wid * 1024 + lane * 16) = sk0; \
;         if constexpr (DQK == 96) { if (wid < 4) *(LAS u32x4*)(kb_ + (8 + wid) * 1024 + lane * 16) = sk1; } \
;     } while (0)
; template <int DQK, int DV, bool DIL, int dl, int SQ0, int SQ1, int SK0, int SK1, int SV, int SO> ...
;     ...
;     const int lane = tid & 63, r32 = lane & 31, hi = lane >> 5; const int wid = __builtin_amdgcn_readfirstlane(tid >> 6);
;     LAS float* wsf = (LAS float*)(lds + WSF_OFF) + wid * 64;
;     const int qrow = q0 + wid * 32 + r32;
;     bf16x8 qf[ND0];
; #pragma unroll
;     for (int d0 = 0; d0 < 4; ++d0) qf[d0] = *(const bf16x8*)(Q0 + (size_t)qrow * (size_t)(SQ0 * dl) + d0 * 16 + hi * 8);
;     if constexpr (DQK == 96) {
; #pragma unroll
;         for (int d0 = 4; d0 < 6; ++d0) qf[d0] = *(const bf16x8*)(Q1 + (size_t)qrow * (size_t)(SQ1 * dl) + (d0 - 4) * 16 + hi * 8);
;     }
;     f32x16 o[NDB];
; #pragma unroll
;     for (int i = 0; i < NDB; ++i) o[i] = (f32x16){0.f, 0.f, 0.f, 0.f, 0.f, 0.f, 0.f, 0.f, 0.f, 0.f, 0.f, 0.f, 0.f, 0.f, 0.f, 0.f};
;     const f32x16 zero16 = (f32x16){0.f, 0.f, 0.f, 0.f, 0.f, 0.f, 0.f, 0.f, 0.f, 0.f, 0.f, 0.f, 0.f, 0.f, 0.f, 0.f};
;     f32x16 negm = zero16;
;     float mrow = 0.f; f32x2 lacc = (f32x2){0.f, 0.f};
;     ...
;     ATT_LOADK(0); ATT_STOREK(0); ATT_LOADK(1); ATT_LOADV(0);
;     __syncthreads();
;     ATT_STOREK(1); ATT_STOREV(0); ATT_LOADK(2); ATT_LOADV(1);
;     if (ATT_NEED(0)) { const LAS unsigned char* kb = lds + KB0 + hi * 1024 + r32 * 16;
; #pragma unroll
;         for (int d0 = 0; d0 < ND0; ++d0) { bf16x8 k0_, k1_; ATT_KRD(k0_, k1_, kb, d0);
;             pa0 = __builtin_amdgcn_mfma_f32_32x32x16_bf16(k0_, qf[d0], d0 == 0 ? zero16 : pa0, 0, 0, 0);
;             pa1 = __builtin_amdgcn_mfma_f32_32x32x16_bf16(k1_, qf[d0], d0 == 0 ? zero16 : pa1, 0, 0, 0); }
.LBB0_227:
	s_ashr_i32 s8, s75, 8
	s_bfe_u32 s11, s75, 0x30005
	s_lshl_b32 s0, s75, 2
	s_ashr_i32 s9, s8, 31
	s_lshl_b32 s78, s11, 7
	s_and_b32 s77, s0, 0x300
	s_lshl_b64 s[12:13], s[8:9], 27
	s_add_u32 s0, s15, s12
	s_addc_u32 s1, s34, s13
	s_add_u32 s36, s0, s78
	s_addc_u32 s37, s1, 0
	s_and_b32 s10, s78, 0x300
	s_add_u32 s38, s0, s10
	v_readfirstlane_b32 s24, v249
	s_addc_u32 s39, s1, 0
	s_lshl_b32 s0, s75, 8
	s_ashr_i32 s40, s24, 6
	s_and_b32 s10, s0, 0x1f00
	s_lshl_b32 s0, s40, 3
	s_ashr_i32 s1, s0, 31
	s_lshl_b64 s[60:61], s[0:1], 1
	s_lshl_b32 s0, s40, 4
	s_and_b32 s0, s0, 48
	v_or_b32_e32 v0, s0, v197
	v_lshlrev_b32_e32 v0, 14, v0
	s_ashr_i32 s1, s24, 3
	v_mov_b32_e32 v217, v1
	v_lshl_add_u64 v[10:11], s[38:39], 0, v[0:1]
	s_and_b32 s38, s1, 0xffffffe0
	v_lshl_add_u64 v[2:3], s[36:37], 0, v[216:217]
	s_ashr_i32 s39, s38, 31
	s_waitcnt vmcnt(3)
	v_lshl_add_u64 v[18:19], v[2:3], 0, s[60:61]
	s_mov_b32 s48, 0x100000
	s_lshl_b64 s[86:87], s[38:39], 1
	v_add_co_u32_e32 v6, vcc, s48, v18
	v_lshl_add_u64 v[10:11], v[10:11], 0, s[86:87]
	v_mov_b32_e32 v207, v1
	v_addc_co_u32_e32 v7, vcc, 0, v19, vcc
	v_lshl_add_u64 v[20:21], v[10:11], 0, v[206:207]
	global_load_dwordx4 v[2:5], v[18:19], off offset:1024
	s_nop 0
	global_load_dwordx4 v[6:9], v[6:7], off offset:1024
	s_nop 0
	global_load_dwordx4 v[10:13], v[20:21], off offset:2048
	global_load_dwordx4 v[14:17], v[20:21], off offset:2176
	s_lshl_b32 s1, s40, 5
	s_add_i32 s10, s1, s10
	s_waitcnt vmcnt(6)
	v_or_b32_e32 v22, s10, v200
	v_ashrrev_i32_e32 v23, 31, v22
	v_lshlrev_b64 v[22:23], 14, v[22:23]
	v_lshlrev_b32_e32 v0, 3, v239
	v_lshl_add_u64 v[22:23], s[36:37], 0, v[22:23]
	v_lshlrev_b32_e32 v208, 1, v0
	v_mov_b32_e32 v209, v1
	v_lshl_add_u64 v[22:23], v[22:23], 0, v[208:209]
	global_load_dwordx4 v[158:161], v[22:23], off
	global_load_dwordx4 v[154:157], v[22:23], off offset:32
	global_load_dwordx4 v[150:153], v[22:23], off offset:64
	global_load_dwordx4 v[146:149], v[22:23], off offset:96
	s_lshl_b32 s1, s40, 10
	v_add_u32_e32 v217, s1, v250
	s_mov_b32 s1, 0x200000
	s_mov_b64 s[46:47], 0x100800
	s_mov_b32 s36, 0
	s_mov_b32 s37, s36
	s_mov_b32 s38, s36
	s_mov_b32 s39, s36
	s_mov_b32 s40, s36
	s_mov_b32 s41, s36
	s_mov_b32 s42, s36
	s_mov_b32 s43, s36
	s_mov_b32 s44, s36
	s_mov_b32 s45, s36
	s_mov_b32 s49, s36
	s_mov_b32 s50, s36
	s_mov_b32 s51, s36
	v_add_lshl_u32 v0, v240, s0, 14
	v_mov_b32_e32 v236, 0
	v_mov_b32_e32 v82, 0
	v_mov_b32_e32 v83, v236
	v_mov_b32_e32 v84, v236
	v_mov_b32_e32 v85, v236
	v_mov_b32_e32 v86, v236
	v_mov_b32_e32 v87, v236
	v_mov_b32_e32 v88, v236
	v_mov_b32_e32 v89, v236
	v_mov_b32_e32 v90, v236
	v_mov_b32_e32 v91, v236
	v_mov_b32_e32 v92, v236
	v_mov_b32_e32 v93, v236
	v_mov_b32_e32 v94, v236
	v_mov_b32_e32 v95, v236
	v_mov_b32_e32 v96, v236
	v_mov_b32_e32 v97, v236
	s_waitcnt vmcnt(7)
	ds_write_b128 v217, v[2:5]
	s_waitcnt lgkmcnt(0)
	s_barrier
	s_waitcnt vmcnt(6)
	ds_write_b128 v217, v[6:9] offset:12288
	s_waitcnt vmcnt(5)
	ds_write_b128 v217, v[10:13] offset:24576
	s_waitcnt vmcnt(4)
	ds_write_b128 v217, v[14:17] offset:32768
	ds_read_b128 v[2:5], v254
	ds_read_b128 v[6:9], v254 offset:512
	s_waitcnt vmcnt(3) lgkmcnt(1)
	v_mfma_f32_32x32x16_bf16 v[98:113], v[2:5], v[158:161], 0
	ds_read_b128 v[2:5], v254 offset:2048
	v_add_co_u32_e32 v10, vcc, s1, v18
	v_lshl_add_u64 v[12:13], v[20:21], 0, s[46:47]
	s_nop 0
	v_addc_co_u32_e32 v11, vcc, 0, v19, vcc
	v_add_co_u32_e32 v14, vcc, s48, v20
	s_waitcnt lgkmcnt(1)
	v_mfma_f32_32x32x16_bf16 v[66:81], v[6:9], v[158:161], 0
	v_addc_co_u32_e32 v15, vcc, 0, v21, vcc
	ds_read_b128 v[6:9], v254 offset:2560
	s_and_b32 s1, s24, 0x3fffffc0
	s_lshl_b32 s1, s1, 2
	s_mov_b32 s46, s36
	s_mov_b32 s47, s36
	s_waitcnt vmcnt(2) lgkmcnt(1)
	v_mfma_f32_32x32x16_bf16 v[98:113], v[2:5], v[154:157], v[98:113]
	ds_read_b128 v[2:5], v254 offset:4096
	global_load_dwordx4 v[166:169], v[14:15], off offset:2048
	global_load_dwordx4 v[162:165], v[10:11], off offset:1024
	global_load_dwordx4 v[170:173], v[12:13], off offset:128
	ds_read_b128 v[18:21], v254 offset:4608
	ds_read_b128 v[22:25], v254 offset:6144
	s_mov_b32 s48, s36
	s_add_i32 s1, s1, 0
	v_lshl_add_u32 v209, v200, 2, s1
	s_waitcnt lgkmcnt(3)
	v_mfma_f32_32x32x16_bf16 v[66:81], v[6:9], v[154:157], v[66:81]
	v_lshl_add_u32 v207, v253, 2, s1
	s_waitcnt vmcnt(4) lgkmcnt(2)
	v_mfma_f32_32x32x16_bf16 v[98:113], v[2:5], v[150:153], v[98:113]
	v_mov_b64_e32 v[2:3], s[36:37]
	v_mov_b64_e32 v[4:5], s[38:39]
	v_mov_b64_e32 v[6:7], s[40:41]
	v_mov_b64_e32 v[8:9], s[42:43]
	v_mov_b64_e32 v[10:11], s[44:45]
	v_mov_b64_e32 v[12:13], s[46:47]
	v_mov_b64_e32 v[14:15], s[48:49]
	s_waitcnt lgkmcnt(1)
	v_mfma_f32_32x32x16_bf16 v[66:81], v[18:21], v[150:153], v[66:81]
	ds_read_b128 v[18:21], v254 offset:6656
	v_mov_b64_e32 v[16:17], s[50:51]
	s_add_u32 s38, s78, s60
	s_addc_u32 s39, 0, s61
	v_lshl_add_u64 v[218:219], v[212:213], 0, s[38:39]
	s_add_u32 s38, s77, s86
	s_addc_u32 s39, 0, s87
	s_waitcnt vmcnt(3) lgkmcnt(1)
	v_mfma_f32_32x32x16_bf16 v[98:113], v[22:25], v[146:149], v[98:113]
	v_lshl_add_u64 v[22:23], s[38:39], 0, v[0:1]
	v_lshl_add_u64 v[220:221], v[214:215], 0, v[22:23]
	v_mov_b64_e32 v[48:49], v[16:17]
	v_mov_b64_e32 v[64:65], v[16:17]
	s_mov_b64 s[42:43], 0x200000
	v_mov_b64_e32 v[46:47], v[14:15]
	v_mov_b64_e32 v[44:45], v[12:13]
	s_waitcnt lgkmcnt(0)
; __device__ __forceinline__ float max3f(float a, float b, float c) { return __builtin_fmaxf(__builtin_fmaxf(a, b), c); }
; template <int DQK, int DV, bool DIL, int dl, int SQ0, int SQ1, int SK0, int SK1, int SV, int SO> ...
;     ...
;         float a_ = -1e30f, b_ = -1e30f;
; #pragma unroll
;         for (int i = 0; i < 8; ++i) { a_ = max3f(a_, pa0[2 * i], pa0[2 * i + 1]); b_ = max3f(b_, pa1[2 * i], pa1[2 * i + 1]); }
;         mxa = __builtin_fmaxf(a_, b_);
;     }
;     __syncthreads();
	v_mfma_f32_32x32x16_bf16 v[66:81], v[18:21], v[146:149], v[66:81]
	s_nop 2
	v_max_f32_e32 v0, v98, v98
	v_max_f32_e32 v0, 0xf149f2ca, v0
	v_max3_f32 v0, v0, v99, v100
	v_max3_f32 v0, v0, v101, v102
	v_max3_f32 v0, v0, v103, v104
	v_max3_f32 v0, v0, v105, v106
	v_max3_f32 v0, v0, v107, v108
	s_nop 1
	v_max3_f32 v18, v66, s25, v67
	v_max3_f32 v18, v18, v68, v69
	v_max3_f32 v18, v18, v70, v71
	v_max3_f32 v18, v18, v72, v73
	v_max3_f32 v18, v18, v74, v75
	v_max3_f32 v18, v18, v76, v77
	v_max3_f32 v18, v18, v78, v79
	v_max3_f32 v0, v0, v109, v110
	v_max3_f32 v18, v18, v80, v81
	v_max3_f32 v0, v0, v111, v112
	v_max3_f32 v114, v0, v113, v18
	v_add_lshl_u32 v0, v252, s0, 14
	v_lshl_add_u64 v[18:19], s[38:39], 0, v[0:1]
	v_lshl_add_u64 v[222:223], v[214:215], 0, v[18:19]
	v_mov_b32_e32 v0, v1
	v_mov_b64_e32 v[32:33], v[16:17]
	v_mov_b64_e32 v[30:31], v[14:15]
	v_mov_b64_e32 v[28:29], v[12:13]
	v_mov_b64_e32 v[26:27], v[10:11]
	v_mov_b64_e32 v[24:25], v[8:9]
	v_mov_b64_e32 v[22:23], v[6:7]
	v_mov_b64_e32 v[20:21], v[4:5]
	v_mov_b64_e32 v[18:19], v[2:3]
	v_mov_b64_e32 v[42:43], v[10:11]
	v_mov_b64_e32 v[40:41], v[8:9]
	v_mov_b64_e32 v[38:39], v[6:7]
	v_mov_b64_e32 v[36:37], v[4:5]
	v_mov_b64_e32 v[34:35], v[2:3]
	v_mov_b64_e32 v[62:63], v[14:15]
	v_mov_b64_e32 v[60:61], v[12:13]
	v_mov_b64_e32 v[58:59], v[10:11]
	v_mov_b64_e32 v[56:57], v[8:9]
	v_mov_b64_e32 v[54:55], v[6:7]
	v_mov_b64_e32 v[52:53], v[4:5]
	v_mov_b64_e32 v[50:51], v[2:3]
	v_mov_b64_e32 v[224:225], v[0:1]
	v_xor_b32_e32 v228, 0x80000000, v236
	v_mov_b32_e32 v229, v228
	v_mov_b64_e32 v[130:131], v[228:229]
	v_mov_b64_e32 v[132:133], v[228:229]
	v_mov_b64_e32 v[134:135], v[228:229]
	v_mov_b64_e32 v[136:137], v[228:229]
	v_mov_b64_e32 v[138:139], v[228:229]
	v_mov_b64_e32 v[140:141], v[228:229]
	v_mov_b64_e32 v[142:143], v[228:229]
	v_mov_b64_e32 v[144:145], v[228:229]
	v_lshl_add_u64 v[190:191], v[218:219], 0, s[12:13]
	v_add_co_u32_e32 v190, vcc, 0x9700000, v190
	s_nop 1
	v_addc_co_u32_e32 v191, vcc, 0, v191, vcc
	v_lshl_add_u64 v[192:193], v[222:223], 0, s[12:13]
	v_add_co_u32_e32 v192, vcc, 0x9400000, v192
	s_nop 1
	v_addc_co_u32_e32 v193, vcc, 0, v193, vcc
	s_barrier
	s_branch .LBB0_229
.LBB0_228:
	v_exp_f32_e32 v116, v116
	v_exp_f32_e32 v117, v117
	v_add_f32_e32 v224, v224, v116
	v_cvt_pk_bf16_f32 v175, v116, v117
	v_add_f32_e32 v225, v225, v117
	s_waitcnt lgkmcnt(4)
	v_mfma_f32_32x32x16_bf16 v[98:113], v[182:185], v[154:157], v[98:113]
	ds_read_b128 v[130:133], v254 offset:4096
	ds_read_b128 v[134:137], v254 offset:4608
	v_exp_f32_e32 v118, v118
	v_exp_f32_e32 v119, v119
	v_add_f32_e32 v224, v224, v118
	v_cvt_pk_bf16_f32 v176, v118, v119
	v_add_f32_e32 v225, v225, v119
	s_waitcnt lgkmcnt(5)
	v_mfma_f32_32x32x16_bf16 v[66:81], v[178:181], v[154:157], v[66:81]
	v_exp_f32_e32 v120, v120
	v_exp_f32_e32 v121, v121
	v_add_f32_e32 v224, v224, v120
	v_cvt_pk_bf16_f32 v177, v120, v121
	v_add_f32_e32 v225, v225, v121
	s_waitcnt lgkmcnt(1)
	v_mfma_f32_32x32x16_bf16 v[98:113], v[130:133], v[150:153], v[98:113]
	ds_read_b128 v[138:141], v254 offset:6144
	ds_read_b128 v[142:145], v254 offset:6656
	v_exp_f32_e32 v122, v122
	v_exp_f32_e32 v123, v123
	v_add_f32_e32 v224, v224, v122
	v_cvt_pk_bf16_f32 v130, v122, v123
	v_add_f32_e32 v225, v225, v123
	s_waitcnt lgkmcnt(2)
	v_mfma_f32_32x32x16_bf16 v[66:81], v[134:137], v[150:153], v[66:81]
	v_exp_f32_e32 v124, v124
	v_exp_f32_e32 v125, v125
	v_add_f32_e32 v224, v224, v124
	v_cvt_pk_bf16_f32 v131, v124, v125
	v_add_f32_e32 v225, v225, v125
	s_waitcnt lgkmcnt(1)
	v_mfma_f32_32x32x16_bf16 v[98:113], v[138:141], v[146:149], v[98:113]
	v_exp_f32_e32 v126, v126
	v_exp_f32_e32 v127, v127
	v_add_f32_e32 v224, v224, v126
	v_cvt_pk_bf16_f32 v132, v126, v127
	v_add_f32_e32 v225, v225, v127
	s_waitcnt lgkmcnt(0)
	v_mfma_f32_32x32x16_bf16 v[66:81], v[142:145], v[146:149], v[66:81]
	v_exp_f32_e32 v128, v128
	v_exp_f32_e32 v129, v129
	v_add_f32_e32 v224, v224, v128
	v_cvt_pk_bf16_f32 v133, v128, v129
	v_add_f32_e32 v225, v225, v129
	ds_read_b64_tr_b16 v[134:135], v243 offset:40960
	ds_read_b64_tr_b16 v[136:137], v243 offset:41472
	ds_read_b64_tr_b16 v[138:139], v243 offset:45056
	ds_read_b64_tr_b16 v[140:141], v243 offset:45568
	s_waitcnt lgkmcnt(2)
	v_mfma_f32_32x32x16_bf16 v[50:65], v[174:177], v[134:137], v[50:65]
	ds_read_b64_tr_b16 v[142:143], v243 offset:49152
	ds_read_b64_tr_b16 v[144:145], v243 offset:49664
	v_exp_f32_e32 v82, v82
	v_exp_f32_e32 v83, v83
	v_add_f32_e32 v224, v224, v82
	v_cvt_pk_bf16_f32 v114, v82, v83
	v_add_f32_e32 v225, v225, v83
	s_waitcnt lgkmcnt(2)
	v_mfma_f32_32x32x16_bf16 v[34:49], v[174:177], v[138:141], v[34:49]
	ds_read_b64_tr_b16 v[134:135], v243 offset:53248
	ds_read_b64_tr_b16 v[136:137], v243 offset:53760
	v_exp_f32_e32 v84, v84
	v_exp_f32_e32 v85, v85
	v_add_f32_e32 v224, v224, v84
	v_cvt_pk_bf16_f32 v115, v84, v85
	v_add_f32_e32 v225, v225, v85
	s_waitcnt lgkmcnt(2)
	v_mfma_f32_32x32x16_bf16 v[18:33], v[174:177], v[142:145], v[18:33]
	ds_read_b64_tr_b16 v[138:139], v243 offset:41984
	ds_read_b64_tr_b16 v[140:141], v243 offset:42496
	v_exp_f32_e32 v86, v86
	v_exp_f32_e32 v87, v87
	v_add_f32_e32 v224, v224, v86
	v_cvt_pk_bf16_f32 v116, v86, v87
	v_add_f32_e32 v225, v225, v87
	s_waitcnt lgkmcnt(2)
	v_mfma_f32_32x32x16_bf16 v[2:17], v[174:177], v[134:137], v[2:17]
	ds_read_b64_tr_b16 v[142:143], v243 offset:46080
	ds_read_b64_tr_b16 v[144:145], v243 offset:46592
	v_exp_f32_e32 v88, v88
	v_exp_f32_e32 v89, v89
	v_add_f32_e32 v224, v224, v88
	v_cvt_pk_bf16_f32 v117, v88, v89
	v_add_f32_e32 v225, v225, v89
	s_waitcnt lgkmcnt(2)
	v_mfma_f32_32x32x16_bf16 v[50:65], v[130:133], v[138:141], v[50:65]
	ds_read_b64_tr_b16 v[134:135], v243 offset:50176
	ds_read_b64_tr_b16 v[136:137], v243 offset:50688
	v_exp_f32_e32 v90, v90
	v_exp_f32_e32 v91, v91
	v_add_f32_e32 v224, v224, v90
	v_cvt_pk_bf16_f32 v118, v90, v91
	v_add_f32_e32 v225, v225, v91
	s_waitcnt lgkmcnt(2)
	v_mfma_f32_32x32x16_bf16 v[34:49], v[130:133], v[142:145], v[34:49]
	ds_read_b64_tr_b16 v[138:139], v243 offset:54272
	ds_read_b64_tr_b16 v[140:141], v243 offset:54784
	v_exp_f32_e32 v92, v92
	v_exp_f32_e32 v93, v93
	v_add_f32_e32 v224, v224, v92
	v_cvt_pk_bf16_f32 v119, v92, v93
	v_add_f32_e32 v225, v225, v93
	s_waitcnt lgkmcnt(2)
	v_mfma_f32_32x32x16_bf16 v[18:33], v[130:133], v[134:137], v[18:33]
	ds_read_b64_tr_b16 v[142:143], v243 offset:43008
	ds_read_b64_tr_b16 v[144:145], v243 offset:43520
	v_exp_f32_e32 v94, v94
	v_exp_f32_e32 v95, v95
	v_add_f32_e32 v224, v224, v94
	v_cvt_pk_bf16_f32 v120, v94, v95
	v_add_f32_e32 v225, v225, v95
	s_waitcnt lgkmcnt(2)
	v_mfma_f32_32x32x16_bf16 v[2:17], v[130:133], v[138:141], v[2:17]
	ds_read_b64_tr_b16 v[134:135], v243 offset:47104
	ds_read_b64_tr_b16 v[136:137], v243 offset:47616
	v_exp_f32_e32 v96, v96
	v_exp_f32_e32 v97, v97
	v_add_f32_e32 v224, v224, v96
	v_cvt_pk_bf16_f32 v121, v96, v97
	v_add_f32_e32 v225, v225, v97
	s_waitcnt lgkmcnt(2)
	v_mfma_f32_32x32x16_bf16 v[50:65], v[114:117], v[142:145], v[50:65]
	ds_read_b64_tr_b16 v[128:129], v243 offset:51200
	ds_read_b64_tr_b16 v[130:131], v243 offset:51712
	v_max_f32_e32 v0, v98, v98
	v_max_f32_e32 v0, 0xf149f2ca, v0
	v_max3_f32 v174, v66, s25, v67
	v_lshl_add_u64 v[218:219], v[218:219], 0, s[42:43]
	v_lshl_add_u64 v[220:221], v[220:221], 0, s[42:43]
	v_lshl_add_u64 v[222:223], v[222:223], 0, s[42:43]
	s_waitcnt lgkmcnt(2)
	v_mfma_f32_32x32x16_bf16 v[34:49], v[114:117], v[134:137], v[34:49]
	ds_read_b64_tr_b16 v[138:139], v243 offset:55296
	ds_read_b64_tr_b16 v[140:141], v243 offset:55808
	v_lshl_add_u64 v[190:191], v[218:219], 0, s[12:13]
	v_add_co_u32_e32 v190, vcc, 0x9700000, v190
	v_max3_f32 v0, v0, v99, v100
	v_max3_f32 v174, v174, v68, v69
	v_addc_co_u32_e32 v191, vcc, 0, v191, vcc
	s_waitcnt lgkmcnt(2)
	v_mfma_f32_32x32x16_bf16 v[18:33], v[114:117], v[128:131], v[18:33]
	ds_read_b64_tr_b16 v[132:133], v243 offset:44032
	ds_read_b64_tr_b16 v[134:135], v243 offset:44544
	v_lshl_add_u64 v[192:193], v[222:223], 0, s[12:13]
	v_add_co_u32_e32 v192, vcc, 0x9400000, v192
	v_max3_f32 v0, v0, v101, v102
	v_max3_f32 v174, v174, v70, v71
	v_addc_co_u32_e32 v193, vcc, 0, v193, vcc
	s_waitcnt lgkmcnt(2)
	v_mfma_f32_32x32x16_bf16 v[2:17], v[114:117], v[138:141], v[2:17]
	ds_read_b64_tr_b16 v[128:129], v243 offset:48128
	ds_read_b64_tr_b16 v[130:131], v243 offset:48640
	v_max3_f32 v0, v0, v103, v104
	v_max3_f32 v174, v174, v72, v73
	s_waitcnt lgkmcnt(2)
	v_mfma_f32_32x32x16_bf16 v[50:65], v[118:121], v[132:135], v[50:65]
	ds_read_b64_tr_b16 v[114:115], v243 offset:52224
	ds_read_b64_tr_b16 v[116:117], v243 offset:52736
	v_max3_f32 v0, v0, v105, v106
	v_max3_f32 v174, v174, v74, v75
	v_mov_b64_e32 v[136:137], v[228:229]
	v_mov_b64_e32 v[138:139], v[228:229]
	s_waitcnt lgkmcnt(2)
	v_mfma_f32_32x32x16_bf16 v[34:49], v[118:121], v[128:131], v[34:49]
	ds_read_b64_tr_b16 v[132:133], v243 offset:56320
	ds_read_b64_tr_b16 v[134:135], v243 offset:56832
	v_max3_f32 v0, v0, v107, v108
	v_max3_f32 v174, v174, v76, v77
	v_mov_b64_e32 v[140:141], v[228:229]
	v_mov_b64_e32 v[142:143], v[228:229]
	s_waitcnt lgkmcnt(2)
	v_mfma_f32_32x32x16_bf16 v[18:33], v[118:121], v[114:117], v[18:33]
	v_max3_f32 v0, v0, v109, v110
	v_max3_f32 v174, v174, v78, v79
	v_mov_b64_e32 v[144:145], v[228:229]
	v_mov_b64_e32 v[130:131], v[228:229]
	s_waitcnt lgkmcnt(0)
	v_mfma_f32_32x32x16_bf16 v[2:17], v[118:121], v[132:135], v[2:17]
	v_max3_f32 v0, v0, v111, v112
	v_max3_f32 v174, v174, v80, v81
	v_mov_b64_e32 v[132:133], v[228:229]
	v_mov_b64_e32 v[134:135], v[228:229]
	s_add_i32 s36, s36, 2
	v_max3_f32 v114, v0, v113, v174
	s_cmpk_gt_u32 s36, 0x7d
	s_barrier
	s_cbranch_scc1 .LBB0_255

.LBB0_233:
	ds_read_b128 v[174:177], v254 offset:12288
	ds_read_b128 v[186:189], v254 offset:12800
	ds_read_b128 v[182:185], v254 offset:14336
	ds_read_b128 v[178:181], v254 offset:14848
	s_waitcnt vmcnt(1)
	ds_write_b128 v217, v[162:165]
	ds_write_b128 v217, v[166:169] offset:40960
	s_waitcnt vmcnt(0)
	ds_write_b128 v217, v[170:173] offset:49152
	global_load_dwordx4 v[162:165], v[190:191], off offset:1024
	global_load_dwordx4 v[170:173], v[192:193], off offset:2048
	global_load_dwordx4 v[166:169], v[192:193], off offset:2176
	v_exp_f32_e32 v98, v98
	v_exp_f32_e32 v99, v99
	s_waitcnt lgkmcnt(6)
	v_mfma_f32_32x32x16_bf16 v[114:129], v[174:177], v[158:161], v[130:145]
	v_add_f32_e32 v224, v224, v98
	v_cvt_pk_bf16_f32 v174, v98, v99
	v_add_f32_e32 v225, v225, v99
	s_waitcnt lgkmcnt(5)
	v_mfma_f32_32x32x16_bf16 v[82:97], v[186:189], v[158:161], v[130:145]
.LBB0_241:
	v_exp_f32_e32 v100, v100
	v_exp_f32_e32 v101, v101
	v_add_f32_e32 v224, v224, v100
	v_cvt_pk_bf16_f32 v175, v100, v101
	v_add_f32_e32 v225, v225, v101
	s_waitcnt lgkmcnt(4)
	v_mfma_f32_32x32x16_bf16 v[114:129], v[182:185], v[154:157], v[114:129]
	ds_read_b128 v[130:133], v254 offset:16384
	ds_read_b128 v[134:137], v254 offset:16896
	v_exp_f32_e32 v102, v102
	v_exp_f32_e32 v103, v103
	v_add_f32_e32 v224, v224, v102
	v_cvt_pk_bf16_f32 v176, v102, v103
	v_add_f32_e32 v225, v225, v103
	s_waitcnt lgkmcnt(5)
	v_mfma_f32_32x32x16_bf16 v[82:97], v[178:181], v[154:157], v[82:97]
	v_exp_f32_e32 v104, v104
	v_exp_f32_e32 v105, v105
	v_add_f32_e32 v224, v224, v104
	v_cvt_pk_bf16_f32 v177, v104, v105
	v_add_f32_e32 v225, v225, v105
	s_waitcnt lgkmcnt(1)
	v_mfma_f32_32x32x16_bf16 v[114:129], v[130:133], v[150:153], v[114:129]
	ds_read_b128 v[138:141], v254 offset:18432
	ds_read_b128 v[142:145], v254 offset:18944
	v_exp_f32_e32 v106, v106
	v_exp_f32_e32 v107, v107
	v_add_f32_e32 v224, v224, v106
	v_cvt_pk_bf16_f32 v130, v106, v107
	v_add_f32_e32 v225, v225, v107
	s_waitcnt lgkmcnt(2)
	v_mfma_f32_32x32x16_bf16 v[82:97], v[134:137], v[150:153], v[82:97]
	v_exp_f32_e32 v108, v108
	v_exp_f32_e32 v109, v109
	v_add_f32_e32 v224, v224, v108
	v_cvt_pk_bf16_f32 v131, v108, v109
	v_add_f32_e32 v225, v225, v109
	s_waitcnt lgkmcnt(1)
	v_mfma_f32_32x32x16_bf16 v[114:129], v[138:141], v[146:149], v[114:129]
	v_exp_f32_e32 v110, v110
	v_exp_f32_e32 v111, v111
	v_add_f32_e32 v224, v224, v110
	v_cvt_pk_bf16_f32 v132, v110, v111
	v_add_f32_e32 v225, v225, v111
	s_waitcnt lgkmcnt(0)
	v_mfma_f32_32x32x16_bf16 v[82:97], v[142:145], v[146:149], v[82:97]
	v_exp_f32_e32 v112, v112
	v_exp_f32_e32 v113, v113
	v_add_f32_e32 v224, v224, v112
	v_cvt_pk_bf16_f32 v133, v112, v113
	v_add_f32_e32 v225, v225, v113
	ds_read_b64_tr_b16 v[134:135], v243 offset:24576
	ds_read_b64_tr_b16 v[136:137], v243 offset:25088
	ds_read_b64_tr_b16 v[138:139], v243 offset:28672
	ds_read_b64_tr_b16 v[140:141], v243 offset:29184
	s_waitcnt lgkmcnt(2)
	v_mfma_f32_32x32x16_bf16 v[50:65], v[174:177], v[134:137], v[50:65]
	ds_read_b64_tr_b16 v[142:143], v243 offset:32768
	ds_read_b64_tr_b16 v[144:145], v243 offset:33280
	v_exp_f32_e32 v66, v66
	v_exp_f32_e32 v67, v67
	v_add_f32_e32 v224, v224, v66
	v_cvt_pk_bf16_f32 v98, v66, v67
	v_add_f32_e32 v225, v225, v67
	s_waitcnt lgkmcnt(2)
	v_mfma_f32_32x32x16_bf16 v[34:49], v[174:177], v[138:141], v[34:49]
	ds_read_b64_tr_b16 v[134:135], v243 offset:36864
	ds_read_b64_tr_b16 v[136:137], v243 offset:37376
	v_exp_f32_e32 v68, v68
	v_exp_f32_e32 v69, v69
	v_add_f32_e32 v224, v224, v68
	v_cvt_pk_bf16_f32 v99, v68, v69
	v_add_f32_e32 v225, v225, v69
	s_waitcnt lgkmcnt(2)
	v_mfma_f32_32x32x16_bf16 v[18:33], v[174:177], v[142:145], v[18:33]
	ds_read_b64_tr_b16 v[138:139], v243 offset:25600
	ds_read_b64_tr_b16 v[140:141], v243 offset:26112
	v_exp_f32_e32 v70, v70
	v_exp_f32_e32 v71, v71
	v_add_f32_e32 v224, v224, v70
	v_cvt_pk_bf16_f32 v100, v70, v71
	v_add_f32_e32 v225, v225, v71
	s_waitcnt lgkmcnt(2)
	v_mfma_f32_32x32x16_bf16 v[2:17], v[174:177], v[134:137], v[2:17]
	ds_read_b64_tr_b16 v[142:143], v243 offset:29696
	ds_read_b64_tr_b16 v[144:145], v243 offset:30208
	v_exp_f32_e32 v72, v72
	v_exp_f32_e32 v73, v73
	v_add_f32_e32 v224, v224, v72
	v_cvt_pk_bf16_f32 v101, v72, v73
	v_add_f32_e32 v225, v225, v73
	s_waitcnt lgkmcnt(2)
	v_mfma_f32_32x32x16_bf16 v[50:65], v[130:133], v[138:141], v[50:65]
	ds_read_b64_tr_b16 v[134:135], v243 offset:33792
	ds_read_b64_tr_b16 v[136:137], v243 offset:34304
	v_exp_f32_e32 v74, v74
	v_exp_f32_e32 v75, v75
	v_add_f32_e32 v224, v224, v74
	v_cvt_pk_bf16_f32 v102, v74, v75
	v_add_f32_e32 v225, v225, v75
	s_waitcnt lgkmcnt(2)
	v_mfma_f32_32x32x16_bf16 v[34:49], v[130:133], v[142:145], v[34:49]
	ds_read_b64_tr_b16 v[138:139], v243 offset:37888
	ds_read_b64_tr_b16 v[140:141], v243 offset:38400
	v_exp_f32_e32 v76, v76
	v_exp_f32_e32 v77, v77
	v_add_f32_e32 v224, v224, v76
	v_cvt_pk_bf16_f32 v103, v76, v77
	v_add_f32_e32 v225, v225, v77
	s_waitcnt lgkmcnt(2)
	v_mfma_f32_32x32x16_bf16 v[18:33], v[130:133], v[134:137], v[18:33]
	ds_read_b64_tr_b16 v[142:143], v243 offset:26624
	ds_read_b64_tr_b16 v[144:145], v243 offset:27136
	v_exp_f32_e32 v78, v78
	v_exp_f32_e32 v79, v79
	v_add_f32_e32 v224, v224, v78
	v_cvt_pk_bf16_f32 v104, v78, v79
	v_add_f32_e32 v225, v225, v79
	s_waitcnt lgkmcnt(2)
	v_mfma_f32_32x32x16_bf16 v[2:17], v[130:133], v[138:141], v[2:17]
	ds_read_b64_tr_b16 v[134:135], v243 offset:30720
	ds_read_b64_tr_b16 v[136:137], v243 offset:31232
	v_exp_f32_e32 v80, v80
	v_exp_f32_e32 v81, v81
	v_add_f32_e32 v224, v224, v80
	v_cvt_pk_bf16_f32 v105, v80, v81
	v_add_f32_e32 v225, v225, v81
	s_waitcnt lgkmcnt(2)
	v_mfma_f32_32x32x16_bf16 v[50:65], v[98:101], v[142:145], v[50:65]
	ds_read_b64_tr_b16 v[130:131], v243 offset:34816
	ds_read_b64_tr_b16 v[132:133], v243 offset:35328
	v_max_f32_e32 v0, v114, v114
	v_max_f32_e32 v0, 0xf149f2ca, v0
	v_max3_f32 v112, v82, s25, v83
	s_waitcnt lgkmcnt(2)
	v_mfma_f32_32x32x16_bf16 v[34:49], v[98:101], v[134:137], v[34:49]
	ds_read_b64_tr_b16 v[138:139], v243 offset:38912
	ds_read_b64_tr_b16 v[140:141], v243 offset:39424
	v_lshl_add_u64 v[190:191], v[218:219], 0, s[12:13]
	v_add_co_u32_e32 v190, vcc, 0x9800000, v190
	v_max3_f32 v0, v0, v115, v116
	v_max3_f32 v112, v112, v84, v85
	v_addc_co_u32_e32 v191, vcc, 0, v191, vcc
	s_waitcnt lgkmcnt(2)
	v_mfma_f32_32x32x16_bf16 v[18:33], v[98:101], v[130:133], v[18:33]
	ds_read_b64_tr_b16 v[134:135], v243 offset:27648
	ds_read_b64_tr_b16 v[136:137], v243 offset:28160
	v_lshl_add_u64 v[192:193], v[220:221], 0, s[12:13]
	v_add_co_u32_e32 v192, vcc, 0x9400000, v192
	v_max3_f32 v0, v0, v117, v118
	v_max3_f32 v112, v112, v86, v87
	v_addc_co_u32_e32 v193, vcc, 0, v193, vcc
	s_waitcnt lgkmcnt(2)
	v_mfma_f32_32x32x16_bf16 v[2:17], v[98:101], v[138:141], v[2:17]
	ds_read_b64_tr_b16 v[130:131], v243 offset:31744
	ds_read_b64_tr_b16 v[132:133], v243 offset:32256
	v_max3_f32 v0, v0, v119, v120
	v_max3_f32 v112, v112, v88, v89
	s_waitcnt lgkmcnt(2)
	v_mfma_f32_32x32x16_bf16 v[50:65], v[102:105], v[134:137], v[50:65]
	ds_read_b64_tr_b16 v[98:99], v243 offset:35840
	ds_read_b64_tr_b16 v[100:101], v243 offset:36352
	v_max3_f32 v0, v0, v121, v122
	v_max3_f32 v112, v112, v90, v91
	v_mov_b64_e32 v[138:139], v[228:229]
	v_mov_b64_e32 v[140:141], v[228:229]
	s_waitcnt lgkmcnt(2)
	v_mfma_f32_32x32x16_bf16 v[34:49], v[102:105], v[130:133], v[34:49]
	ds_read_b64_tr_b16 v[134:135], v243 offset:39936
	ds_read_b64_tr_b16 v[136:137], v243 offset:40448
	v_max3_f32 v0, v0, v123, v124
	v_max3_f32 v112, v112, v92, v93
	v_mov_b64_e32 v[142:143], v[228:229]
	v_mov_b64_e32 v[144:145], v[228:229]
	s_waitcnt lgkmcnt(2)
	v_mfma_f32_32x32x16_bf16 v[18:33], v[102:105], v[98:101], v[18:33]
	v_max3_f32 v0, v0, v125, v126
	v_max3_f32 v112, v112, v94, v95
	v_mov_b64_e32 v[130:131], v[228:229]
	v_mov_b64_e32 v[132:133], v[228:229]
	s_waitcnt lgkmcnt(0)
	v_mfma_f32_32x32x16_bf16 v[2:17], v[102:105], v[134:137], v[2:17]
	v_max3_f32 v0, v0, v127, v128
	v_max3_f32 v112, v112, v96, v97
	v_mov_b64_e32 v[134:135], v[228:229]
	v_mov_b64_e32 v[136:137], v[228:229]
	v_max3_f32 v0, v0, v129, v112
	v_cmp_lt_f32_e32 vcc, s16, v0
	s_barrier
	s_cbranch_vccz .LBB0_245
	ds_bpermute_b32 v98, v251, v0
	s_waitcnt lgkmcnt(0)
	v_max3_f32 v98, v0, v98, 0
	v_exp_f32_e64 v0, -v98
	s_and_saveexec_b64 s[38:39], s[6:7]
	ds_write_b32 v209, v0 offset:57344
	s_or_b64 exec, exec, s[38:39]
	v_sub_f32_e32 v129, v129, v98
	v_sub_f32_e32 v128, v128, v98
	v_sub_f32_e32 v127, v127, v98
	v_sub_f32_e32 v126, v126, v98
	v_sub_f32_e32 v125, v125, v98
	v_sub_f32_e32 v124, v124, v98
	v_sub_f32_e32 v123, v123, v98
	v_sub_f32_e32 v122, v122, v98
	v_sub_f32_e32 v121, v121, v98
	v_sub_f32_e32 v120, v120, v98
	v_sub_f32_e32 v119, v119, v98
	v_sub_f32_e32 v118, v118, v98
	v_sub_f32_e32 v117, v117, v98
	v_sub_f32_e32 v116, v116, v98
	v_sub_f32_e32 v115, v115, v98
	v_sub_f32_e32 v114, v114, v98
	v_sub_f32_e32 v82, v82, v98
	v_sub_f32_e32 v83, v83, v98
	v_sub_f32_e32 v84, v84, v98
	v_sub_f32_e32 v85, v85, v98
	v_sub_f32_e32 v86, v86, v98
	v_sub_f32_e32 v87, v87, v98
	v_sub_f32_e32 v88, v88, v98
	v_sub_f32_e32 v89, v89, v98
	v_sub_f32_e32 v90, v90, v98
	v_sub_f32_e32 v91, v91, v98
	v_sub_f32_e32 v92, v92, v98
	v_sub_f32_e32 v93, v93, v98
	v_sub_f32_e32 v94, v94, v98
	v_sub_f32_e32 v95, v95, v98
	v_sub_f32_e32 v96, v96, v98
	v_sub_f32_e32 v97, v97, v98
	v_add_f32_e32 v236, v236, v98
	ds_read_b128 v[98:101], v207 offset:57344
	ds_read_b128 v[102:105], v207 offset:57376
	ds_read_b128 v[106:109], v207 offset:57408
	ds_read_b128 v[110:113], v207 offset:57440
	v_pk_mul_f32 v[224:225], v[224:225], v[0:1] op_sel_hi:[1,0]
	s_waitcnt lgkmcnt(3)
	v_pk_mul_f32 v[52:53], v[52:53], v[100:101]
	s_waitcnt lgkmcnt(2)
	v_pk_mul_f32 v[56:57], v[56:57], v[104:105]
	s_waitcnt lgkmcnt(1)
	v_pk_mul_f32 v[60:61], v[60:61], v[108:109]
	s_waitcnt lgkmcnt(0)
	v_pk_mul_f32 v[64:65], v[64:65], v[112:113]
	v_pk_mul_f32 v[62:63], v[62:63], v[110:111]
	v_pk_mul_f32 v[58:59], v[58:59], v[106:107]
	v_pk_mul_f32 v[54:55], v[54:55], v[102:103]
	v_pk_mul_f32 v[50:51], v[50:51], v[98:99]
	v_pk_mul_f32 v[48:49], v[48:49], v[112:113]
	v_pk_mul_f32 v[44:45], v[44:45], v[108:109]
	v_pk_mul_f32 v[40:41], v[40:41], v[104:105]
	v_pk_mul_f32 v[36:37], v[36:37], v[100:101]
	v_pk_mul_f32 v[46:47], v[46:47], v[110:111]
	v_pk_mul_f32 v[42:43], v[42:43], v[106:107]
	v_pk_mul_f32 v[38:39], v[38:39], v[102:103]
	v_pk_mul_f32 v[34:35], v[34:35], v[98:99]
	v_pk_mul_f32 v[32:33], v[32:33], v[112:113]
	v_pk_mul_f32 v[28:29], v[28:29], v[108:109]
	v_pk_mul_f32 v[24:25], v[24:25], v[104:105]
	v_pk_mul_f32 v[20:21], v[20:21], v[100:101]
	v_pk_mul_f32 v[30:31], v[30:31], v[110:111]
	v_pk_mul_f32 v[26:27], v[26:27], v[106:107]
	v_pk_mul_f32 v[22:23], v[22:23], v[102:103]
	v_pk_mul_f32 v[18:19], v[18:19], v[98:99]
	v_pk_mul_f32 v[16:17], v[16:17], v[112:113]
	v_pk_mul_f32 v[12:13], v[12:13], v[108:109]
	v_pk_mul_f32 v[8:9], v[8:9], v[104:105]
	v_pk_mul_f32 v[4:5], v[4:5], v[100:101]
	v_pk_mul_f32 v[14:15], v[14:15], v[110:111]
	v_pk_mul_f32 v[10:11], v[10:11], v[106:107]
	v_pk_mul_f32 v[6:7], v[6:7], v[102:103]
	v_pk_mul_f32 v[2:3], v[2:3], v[98:99]
	v_xor_b32_e32 v228, 0x80000000, v236
	v_mov_b32_e32 v229, v228
	v_mov_b64_e32 v[130:131], v[228:229]
	v_mov_b64_e32 v[132:133], v[228:229]
	v_mov_b64_e32 v[134:135], v[228:229]
	v_mov_b64_e32 v[136:137], v[228:229]
	v_mov_b64_e32 v[138:139], v[228:229]
	v_mov_b64_e32 v[140:141], v[228:229]
	v_mov_b64_e32 v[142:143], v[228:229]
	v_mov_b64_e32 v[144:145], v[228:229]
.LBB0_245:
	ds_read_b128 v[174:177], v254
	ds_read_b128 v[186:189], v254 offset:512
	ds_read_b128 v[182:185], v254 offset:2048
	ds_read_b128 v[178:181], v254 offset:2560
	s_cmpk_gt_u32 s36, 0x7b
	s_waitcnt vmcnt(2)
	ds_write_b128 v217, v[162:165] offset:12288
	s_waitcnt vmcnt(1)
	ds_write_b128 v217, v[170:173] offset:24576
	s_waitcnt vmcnt(0)
	ds_write_b128 v217, v[166:169] offset:32768
	s_cbranch_scc1 .LBB0_247
	global_load_dwordx4 v[162:165], v[190:191], off offset:1024
.LBB0_247:
	global_load_dwordx4 v[166:169], v[192:193], off offset:2048
	global_load_dwordx4 v[170:173], v[192:193], off offset:2176
	v_exp_f32_e32 v114, v114
	v_exp_f32_e32 v115, v115
	s_waitcnt lgkmcnt(6)
	v_mfma_f32_32x32x16_bf16 v[98:113], v[174:177], v[158:161], v[130:145]
	v_add_f32_e32 v224, v224, v114
	v_cvt_pk_bf16_f32 v174, v114, v115
	v_add_f32_e32 v225, v225, v115
	s_waitcnt lgkmcnt(5)
	v_mfma_f32_32x32x16_bf16 v[66:81], v[186:189], v[158:161], v[130:145]
	s_branch .LBB0_228
